# layer-1 table conversion: first 10240 rows done in P4 by the transposing blocks (separate CUs from the prompt scan), rest in P13
# baseline (speedup 1.0000x reference)
.LBB0_1424:
	v_lshl_add_u32 v2, s10, 2, v2
	v_add_u32_e32 v2, 0x8000, v2
	s_mov_b32 s0, 0xa800
	v_cmp_gt_i32_e32 vcc, s0, v2
	s_and_saveexec_b64 s[4:5], vcc
	s_cbranch_execz .LBB0_1429
	v_ashrrev_i32_e32 v3, 31, v2
	s_waitcnt vmcnt(6)
	v_and_b32_e32 v1, 63, v26
	v_lshlrev_b64 v[8:9], 9, v[2:3]
	v_readlane_b32 s16, v245, 7
	s_lshl_b32 s6, s2, 2
	v_lshl_or_b32 v8, v1, 3, v8
	v_readlane_b32 s18, v245, 9
	v_lshlrev_b32_e32 v4, 2, v1
	v_mov_b32_e32 v5, 0
	v_lshl_add_u64 v[6:7], v[2:3], 2, s[82:83]
	s_mov_b64 s[8:9], 0xa310800
	s_ashr_i32 s7, s6, 31
	v_lshl_add_u64 v[8:9], s[82:83], 0, v[8:9]
	s_mov_b64 s[12:13], 0x4280000
	v_readlane_b32 s17, v245, 8
	s_lshl_b32 s3, s18, 12
	v_cmp_eq_u32_e64 s[0:1], 0, v1
	v_lshl_add_u64 v[6:7], v[6:7], 0, s[8:9]
	s_lshl_b64 s[8:9], s[6:7], 2
	v_lshl_add_u64 v[8:9], v[8:9], 0, s[12:13]
	s_lshl_b64 s[12:13], s[6:7], 9
	v_lshlrev_b32_e32 v1, 10, v2
	s_add_i32 s3, s3, 0xfff80000
	s_mov_b64 s[16:17], 0
	v_mov_b32_e32 v3, s79
	v_mov_b32_e32 v12, s77
	v_mov_b32_e32 v13, s78
	v_mov_b32_e32 v14, s76
	v_lshlrev_b32_e32 v10, 4, v4
	v_mov_b32_e32 v11, v5
	s_mov_b32 s7, 0x40c00000
	s_mov_b32 s11, 0xa7ff
	v_readlane_b32 s19, v245, 10
	s_branch .LBB0_1427

.LBB0_2653:
	v_readlane_b32 s0, v245, 0
	s_lshl_b32 s0, s0, 2
	v_lshrrev_b32_e32 v2, 6, v1
	s_add_u32 s0, s0, 0xa400
	v_add_u32_e32 v2, s0, v2
	s_mov_b32 s0, 0x10000
	v_cmp_gt_i32_e32 vcc, s0, v2
	v_readlane_b32 s1, v245, 1
	s_and_saveexec_b64 s[2:3], vcc
	s_cbranch_execz .LBB0_2658
	v_readlane_b32 s8, v245, 7
	v_readlane_b32 s10, v245, 9
	v_ashrrev_i32_e32 v3, 31, v2
	s_waitcnt vmcnt(10)
	v_and_b32_e32 v10, 63, v1
	s_lshl_b32 s4, s10, 2
	s_waitcnt vmcnt(9)
	v_lshlrev_b64 v[8:9], 9, v[2:3]
	v_readlane_b32 s9, v245, 8
	s_addk_i32 s4, 0xfc00
	v_lshl_or_b32 v8, v10, 3, v8
	v_lshl_add_u64 v[6:7], v[2:3], 2, s[50:51]
	s_mov_b64 s[6:7], 0xa310800
	s_ashr_i32 s5, s4, 31
	v_lshl_add_u64 v[8:9], s[50:51], 0, v[8:9]
	s_mov_b64 s[8:9], 0x4280000
	v_lshlrev_b32_e32 v4, 2, v10
	v_mov_b32_e32 v5, 0
	v_readlane_b32 s11, v245, 10
	v_lshl_add_u64 v[6:7], v[6:7], 0, s[6:7]
	s_lshl_b64 s[6:7], s[4:5], 2
	v_lshl_add_u64 v[8:9], v[8:9], 0, s[8:9]
	s_lshl_b64 s[8:9], s[4:5], 9
	s_lshl_b32 s5, s10, 12
	v_cmp_eq_u32_e64 s[0:1], 0, v10
	v_lshlrev_b32_e32 v3, 10, v2
	s_add_i32 s5, s5, 0xfff00000
	s_mov_b64 s[10:11], 0
	v_mov_b32_e32 v12, s47
	v_mov_b32_e32 v13, s45
	v_mov_b32_e32 v14, s46
	v_mov_b32_e32 v15, s44
	v_lshlrev_b32_e32 v10, 4, v4
	v_mov_b32_e32 v11, v5
	s_mov_b32 s14, 0x40c00000
	s_mov_b32 s15, 0xffff
	s_branch .LBB0_2656
